# o26 with 8 filler pulls per idle workgroup (all FFN2/w_o weight conversion leaves the MIX1 queue and runs in WIN's idle last round)
# speedup vs baseline: 1.0184x; 1.0021x over previous
.LBB0_1169:
	s_waitcnt vmcnt(0)
	v_readlane_b32 s80, v254, 8
	v_readlane_b32 s81, v254, 9
	v_readlane_b32 s82, v254, 10
	v_readlane_b32 s83, v254, 11
	v_readlane_b32 s84, v254, 12
	v_readlane_b32 s85, v254, 13
	v_readlane_b32 s86, v254, 14
	v_readlane_b32 s87, v254, 15
	s_barrier
	v_readlane_b32 s101, v253, 0
	s_nop 3
	s_cmpk_lt_u32 s101, 0x61
	s_cbranch_scc1 .LBB0_1170
	s_mov_b32 s99, 1
	s_movk_i32 s98, 0x410
	s_movk_i32 s100, 0x9
	s_add_u32 s0, s86, 0xc800
	s_addc_u32 s1, s87, 0
	v_writelane_b32 v254, s0, 22
	v_mov_b32_e32 v1, v0
	s_branch .Lmix1_entry
